# group-scope GATE0-QKV seam; SGU epilogue loads hoisted and batched; SGU MFMA section rewritten as straight per-k-step batches
# speedup vs baseline: 1.0328x; 1.0151x over previous
.LBB0_434:
	s_or_b64 exec, exec, s[72:73]
	s_and_b32 s72, s89, 1
	s_or_b32 s74, s72, s88
	s_and_b32 s75, s93, 7
	s_and_b64 s[72:73], s[2:3], exec
	s_cselect_b32 s72, s74, s75
	s_ashr_i32 s73, s72, 31
	s_lshl_b64 s[74:75], s[72:73], 16
	v_lshl_add_u64 v[22:23], v[114:115], 0, s[74:75]
	v_lshl_add_u64 v[2:3], v[116:117], 2, v[22:23]
	s_waitcnt vmcnt(0) lgkmcnt(0)
	s_barrier
	global_load_dwordx4 v[10:13], v[2:3], off
	v_lshl_add_u64 v[6:7], v[122:123], 2, v[22:23]
	global_load_dwordx4 v[6:9], v[6:7], off
	v_lshl_add_u64 v[2:3], v[118:119], 2, v[22:23]
	global_load_dwordx4 v[14:17], v[2:3], off
	ds_read_b128 v[18:21], v147
	v_readlane_b32 s64, v249, 58
	v_readlane_b32 s65, v249, 59
	v_or_b32_e32 v24, s33, v141
	v_ashrrev_i32_e32 v25, 31, v24
	v_lshlrev_b64 v[24:25], 12, v[24:25]
	s_lshl_b32 s96, s72, 7
	v_lshl_add_u64 v[24:25], s[80:81], 0, v[24:25]
	s_ashr_i32 s97, s96, 31
	v_lshl_add_u64 v[26:27], s[96:97], 1, v[24:25]
	s_andn2_b64 vcc, exec, s[86:87]
	s_waitcnt vmcnt(2) lgkmcnt(0)
	v_mul_f32_e32 v10, v10, v18
	v_cndmask_b32_e64 v10, v10, 0, s[64:65]
	v_readlane_b32 s64, v249, 60
	v_mul_f32_e32 v12, v12, v20
	v_readlane_b32 s65, v249, 61
	v_mul_f32_e32 v11, v11, v19
	v_mul_f32_e32 v13, v13, v21
	v_cndmask_b32_e64 v12, v12, 0, s[64:65]
	v_readlane_b32 s64, v249, 62
	v_readlane_b32 s65, v249, 63
	v_cndmask_b32_e64 v13, v13, 0, s[12:13]
	v_and_b32_sdwa v20, v13, v166 dst_sel:DWORD dst_unused:UNUSED_PAD src0_sel:WORD_1 src1_sel:DWORD
	v_cndmask_b32_e64 v11, 0, v11, s[64:65]
	v_and_b32_sdwa v21, v11, v166 dst_sel:DWORD dst_unused:UNUSED_PAD src0_sel:WORD_1 src1_sel:DWORD
	v_and_b32_sdwa v18, v12, v166 dst_sel:DWORD dst_unused:UNUSED_PAD src0_sel:WORD_1 src1_sel:DWORD
	v_and_b32_sdwa v19, v10, v166 dst_sel:DWORD dst_unused:UNUSED_PAD src0_sel:WORD_1 src1_sel:DWORD
	v_add3_u32 v13, v13, v20, s92
	v_add3_u32 v11, v11, v21, s92
	v_add3_u32 v10, v10, v19, s92
	v_add3_u32 v12, v12, v18, s92
	v_and_b32_e32 v13, 0xffff0000, v13
	v_and_b32_e32 v18, 0xffff0000, v11
	v_or_b32_sdwa v11, v13, v12 dst_sel:DWORD dst_unused:UNUSED_PAD src0_sel:DWORD src1_sel:WORD_1
	v_or_b32_sdwa v10, v18, v10 dst_sel:DWORD dst_unused:UNUSED_PAD src0_sel:DWORD src1_sel:WORD_1
	ds_write_b64 v150, v[10:11]
	v_lshl_add_u64 v[10:11], v[124:125], 2, v[22:23]
	global_load_dwordx4 v[10:13], v[10:11], off
	v_lshl_add_u64 v[2:3], v[120:121], 2, v[22:23]
	global_load_dwordx4 v[2:5], v[2:3], off
	ds_read_b128 v[18:21], v147
	s_waitcnt vmcnt(2) lgkmcnt(0)
	v_mul_f32_e32 v15, v15, v19
	v_mul_f32_e32 v17, v17, v21
	v_mul_f32_e32 v16, v16, v20
	v_mul_f32_e32 v14, v14, v18
	v_cndmask_b32_e64 v15, 0, v15, s[18:19]
	v_cndmask_b32_e64 v17, v17, 0, s[20:21]
	v_cndmask_b32_e64 v14, v14, 0, s[14:15]
	v_cndmask_b32_e64 v16, v16, 0, s[16:17]
	v_and_b32_sdwa v20, v17, v166 dst_sel:DWORD dst_unused:UNUSED_PAD src0_sel:WORD_1 src1_sel:DWORD
	v_and_b32_sdwa v21, v15, v166 dst_sel:DWORD dst_unused:UNUSED_PAD src0_sel:WORD_1 src1_sel:DWORD
	v_and_b32_sdwa v18, v16, v166 dst_sel:DWORD dst_unused:UNUSED_PAD src0_sel:WORD_1 src1_sel:DWORD
	v_and_b32_sdwa v19, v14, v166 dst_sel:DWORD dst_unused:UNUSED_PAD src0_sel:WORD_1 src1_sel:DWORD
	v_add3_u32 v17, v17, v20, s92
	v_add3_u32 v15, v15, v21, s92
	v_add3_u32 v14, v14, v19, s92
	v_add3_u32 v16, v16, v18, s92
	v_and_b32_e32 v17, 0xffff0000, v17
	v_and_b32_e32 v18, 0xffff0000, v15
	v_or_b32_sdwa v15, v17, v16 dst_sel:DWORD dst_unused:UNUSED_PAD src0_sel:DWORD src1_sel:WORD_1
	v_or_b32_sdwa v14, v18, v14 dst_sel:DWORD dst_unused:UNUSED_PAD src0_sel:DWORD src1_sel:WORD_1
	ds_write_b64 v151, v[14:15]
	v_lshl_add_u64 v[14:15], v[126:127], 2, v[22:23]
	global_load_dwordx4 v[14:17], v[14:15], off
	ds_read_b128 v[18:21], v147
	s_waitcnt vmcnt(1) lgkmcnt(0)
	v_mul_f32_e32 v3, v3, v19
	v_mul_f32_e32 v5, v5, v21
	v_mul_f32_e32 v4, v4, v20
	v_mul_f32_e32 v2, v2, v18
	v_cndmask_b32_e64 v3, 0, v3, s[26:27]
	v_cndmask_b32_e64 v5, v5, 0, s[28:29]
	v_cndmask_b32_e64 v2, v2, 0, s[22:23]
	v_cndmask_b32_e64 v4, v4, 0, s[24:25]
	v_and_b32_sdwa v20, v5, v166 dst_sel:DWORD dst_unused:UNUSED_PAD src0_sel:WORD_1 src1_sel:DWORD
	v_and_b32_sdwa v21, v3, v166 dst_sel:DWORD dst_unused:UNUSED_PAD src0_sel:WORD_1 src1_sel:DWORD
	v_and_b32_sdwa v18, v4, v166 dst_sel:DWORD dst_unused:UNUSED_PAD src0_sel:WORD_1 src1_sel:DWORD
	v_and_b32_sdwa v19, v2, v166 dst_sel:DWORD dst_unused:UNUSED_PAD src0_sel:WORD_1 src1_sel:DWORD
	v_add3_u32 v5, v5, v20, s92
	v_add3_u32 v3, v3, v21, s92
	v_add3_u32 v2, v2, v19, s92
	v_add3_u32 v4, v4, v18, s92
	v_and_b32_e32 v5, 0xffff0000, v5
	v_and_b32_e32 v18, 0xffff0000, v3
	v_or_b32_sdwa v3, v5, v4 dst_sel:DWORD dst_unused:UNUSED_PAD src0_sel:DWORD src1_sel:WORD_1
	v_or_b32_sdwa v2, v18, v2 dst_sel:DWORD dst_unused:UNUSED_PAD src0_sel:DWORD src1_sel:WORD_1
	ds_write_b64 v152, v[2:3]
	ds_read_b128 v[18:21], v147
	v_lshl_add_u64 v[2:3], v[128:129], 2, v[22:23]
	global_load_dwordx4 v[2:5], v[2:3], off
	s_waitcnt lgkmcnt(0)
	v_mul_f32_e32 v7, v7, v19
	v_mul_f32_e32 v9, v9, v21
	v_mul_f32_e32 v8, v8, v20
	v_mul_f32_e32 v6, v6, v18
	v_cndmask_b32_e64 v7, 0, v7, s[36:37]
	v_cndmask_b32_e64 v9, v9, 0, s[38:39]
	v_cndmask_b32_e64 v6, v6, 0, s[30:31]
	v_cndmask_b32_e64 v8, v8, 0, s[34:35]
	v_and_b32_sdwa v20, v9, v166 dst_sel:DWORD dst_unused:UNUSED_PAD src0_sel:WORD_1 src1_sel:DWORD
	v_and_b32_sdwa v21, v7, v166 dst_sel:DWORD dst_unused:UNUSED_PAD src0_sel:WORD_1 src1_sel:DWORD
	v_and_b32_sdwa v18, v8, v166 dst_sel:DWORD dst_unused:UNUSED_PAD src0_sel:WORD_1 src1_sel:DWORD
	v_and_b32_sdwa v19, v6, v166 dst_sel:DWORD dst_unused:UNUSED_PAD src0_sel:WORD_1 src1_sel:DWORD
	v_add3_u32 v9, v9, v20, s92
	v_add3_u32 v7, v7, v21, s92
	v_add3_u32 v6, v6, v19, s92
	v_add3_u32 v8, v8, v18, s92
	v_and_b32_e32 v9, 0xffff0000, v9
	v_and_b32_e32 v18, 0xffff0000, v7
	v_or_b32_sdwa v7, v9, v8 dst_sel:DWORD dst_unused:UNUSED_PAD src0_sel:DWORD src1_sel:WORD_1
	v_or_b32_sdwa v6, v18, v6 dst_sel:DWORD dst_unused:UNUSED_PAD src0_sel:DWORD src1_sel:WORD_1
	ds_write_b64 v153, v[6:7]
	ds_read_b128 v[18:21], v147
	v_lshl_add_u64 v[6:7], v[130:131], 2, v[22:23]
	global_load_dwordx4 v[6:9], v[6:7], off
	s_waitcnt lgkmcnt(0)
	v_mul_f32_e32 v11, v11, v19
	v_mul_f32_e32 v13, v13, v21
	v_mul_f32_e32 v12, v12, v20
	v_mul_f32_e32 v10, v10, v18
	v_cndmask_b32_e64 v11, 0, v11, s[44:45]
	v_cndmask_b32_e64 v13, v13, 0, s[46:47]
	v_cndmask_b32_e64 v10, v10, 0, s[40:41]
	v_cndmask_b32_e64 v12, v12, 0, s[42:43]
	v_and_b32_sdwa v20, v13, v166 dst_sel:DWORD dst_unused:UNUSED_PAD src0_sel:WORD_1 src1_sel:DWORD
	v_and_b32_sdwa v21, v11, v166 dst_sel:DWORD dst_unused:UNUSED_PAD src0_sel:WORD_1 src1_sel:DWORD
	v_and_b32_sdwa v18, v12, v166 dst_sel:DWORD dst_unused:UNUSED_PAD src0_sel:WORD_1 src1_sel:DWORD
	v_and_b32_sdwa v19, v10, v166 dst_sel:DWORD dst_unused:UNUSED_PAD src0_sel:WORD_1 src1_sel:DWORD
	v_add3_u32 v13, v13, v20, s92
	v_add3_u32 v11, v11, v21, s92
	v_add3_u32 v10, v10, v19, s92
	v_add3_u32 v12, v12, v18, s92
	v_and_b32_e32 v13, 0xffff0000, v13
	v_and_b32_e32 v18, 0xffff0000, v11
	v_or_b32_sdwa v11, v13, v12 dst_sel:DWORD dst_unused:UNUSED_PAD src0_sel:DWORD src1_sel:WORD_1
	v_or_b32_sdwa v10, v18, v10 dst_sel:DWORD dst_unused:UNUSED_PAD src0_sel:DWORD src1_sel:WORD_1
	v_lshl_add_u64 v[18:19], v[132:133], 1, v[26:27]
	ds_write_b64 v154, v[10:11]
	global_load_dwordx4 v[18:21], v[18:19], off offset:2048
	ds_read_b128 v[10:13], v147
	s_waitcnt vmcnt(3) lgkmcnt(0)
	v_mul_f32_e32 v22, v15, v11
	v_mul_f32_e32 v11, v16, v12
	v_mul_f32_e32 v10, v14, v10
	v_cndmask_b32_e64 v12, v10, 0, s[48:49]
	v_cndmask_b32_e64 v23, v11, 0, s[50:51]
	v_lshl_add_u64 v[10:11], v[134:135], 1, v[26:27]
	v_mul_f32_e32 v13, v17, v13
	global_load_dwordx4 v[14:17], v[10:11], off offset:2048
	v_and_b32_sdwa v10, v23, v166 dst_sel:DWORD dst_unused:UNUSED_PAD src0_sel:WORD_1 src1_sel:DWORD
	v_and_b32_sdwa v11, v12, v166 dst_sel:DWORD dst_unused:UNUSED_PAD src0_sel:WORD_1 src1_sel:DWORD
	v_add3_u32 v29, v12, v11, s92
	v_add3_u32 v30, v23, v10, s92
	v_lshl_add_u64 v[10:11], v[136:137], 1, v[26:27]
	v_cndmask_b32_e64 v28, 0, v22, s[52:53]
	global_load_dwordx4 v[22:25], v[10:11], off offset:2048
	v_cndmask_b32_e64 v13, v13, 0, s[54:55]
	v_and_b32_sdwa v10, v13, v166 dst_sel:DWORD dst_unused:UNUSED_PAD src0_sel:WORD_1 src1_sel:DWORD
	v_and_b32_sdwa v11, v28, v166 dst_sel:DWORD dst_unused:UNUSED_PAD src0_sel:WORD_1 src1_sel:DWORD
	v_add3_u32 v10, v13, v10, s92
	v_add3_u32 v11, v28, v11, s92
	v_and_b32_e32 v28, 0xffff0000, v10
	v_and_b32_e32 v31, 0xffff0000, v11
	v_lshl_add_u64 v[10:11], v[138:139], 1, v[26:27]
	global_load_dwordx4 v[10:13], v[10:11], off offset:2048
	v_or_b32_sdwa v27, v28, v30 dst_sel:DWORD dst_unused:UNUSED_PAD src0_sel:DWORD src1_sel:WORD_1
	v_or_b32_sdwa v26, v31, v29 dst_sel:DWORD dst_unused:UNUSED_PAD src0_sel:DWORD src1_sel:WORD_1
	ds_write_b64 v155, v[26:27]
	ds_read_b128 v[26:29], v147
	s_waitcnt vmcnt(5) lgkmcnt(0)
	v_mul_f32_e32 v4, v4, v28
	v_mul_f32_e32 v2, v2, v26
	v_mul_f32_e32 v3, v3, v27
	v_mul_f32_e32 v5, v5, v29
	v_cndmask_b32_e64 v2, v2, 0, s[56:57]
	v_cndmask_b32_e64 v4, v4, 0, s[58:59]
	v_cndmask_b32_e64 v3, 0, v3, s[60:61]
	v_cndmask_b32_e64 v5, v5, 0, s[62:63]
	v_and_b32_sdwa v26, v4, v166 dst_sel:DWORD dst_unused:UNUSED_PAD src0_sel:WORD_1 src1_sel:DWORD
	v_and_b32_sdwa v27, v2, v166 dst_sel:DWORD dst_unused:UNUSED_PAD src0_sel:WORD_1 src1_sel:DWORD
	v_add3_u32 v2, v2, v27, s92
	v_add3_u32 v4, v4, v26, s92
	v_and_b32_sdwa v26, v5, v166 dst_sel:DWORD dst_unused:UNUSED_PAD src0_sel:WORD_1 src1_sel:DWORD
	v_and_b32_sdwa v27, v3, v166 dst_sel:DWORD dst_unused:UNUSED_PAD src0_sel:WORD_1 src1_sel:DWORD
	v_add3_u32 v5, v5, v26, s92
	v_add3_u32 v3, v3, v27, s92
	v_and_b32_e32 v5, 0xffff0000, v5
	v_and_b32_e32 v26, 0xffff0000, v3
	v_or_b32_sdwa v3, v5, v4 dst_sel:DWORD dst_unused:UNUSED_PAD src0_sel:DWORD src1_sel:WORD_1
	v_or_b32_sdwa v2, v26, v2 dst_sel:DWORD dst_unused:UNUSED_PAD src0_sel:DWORD src1_sel:WORD_1
	ds_write_b64 v156, v[2:3]
	ds_read_b128 v[2:5], v147
	s_waitcnt vmcnt(4) lgkmcnt(0)
	v_mul_f32_e32 v4, v8, v4
	v_mul_f32_e32 v2, v6, v2
	v_mul_f32_e32 v3, v7, v3
	v_mul_f32_e32 v5, v9, v5
	v_cndmask_b32_e64 v2, v2, 0, s[4:5]
	v_cndmask_b32_e64 v4, v4, 0, s[6:7]
	v_cndmask_b32_e64 v3, 0, v3, s[8:9]
	v_cndmask_b32_e64 v5, v5, 0, s[10:11]
	v_and_b32_sdwa v6, v4, v166 dst_sel:DWORD dst_unused:UNUSED_PAD src0_sel:WORD_1 src1_sel:DWORD
	v_and_b32_sdwa v7, v2, v166 dst_sel:DWORD dst_unused:UNUSED_PAD src0_sel:WORD_1 src1_sel:DWORD
	v_add3_u32 v2, v2, v7, s92
	v_add3_u32 v4, v4, v6, s92
	v_and_b32_sdwa v6, v5, v166 dst_sel:DWORD dst_unused:UNUSED_PAD src0_sel:WORD_1 src1_sel:DWORD
	v_and_b32_sdwa v7, v3, v166 dst_sel:DWORD dst_unused:UNUSED_PAD src0_sel:WORD_1 src1_sel:DWORD
	v_add3_u32 v5, v5, v6, s92
	v_add3_u32 v3, v3, v7, s92
	v_and_b32_e32 v5, 0xffff0000, v5
	v_and_b32_e32 v6, 0xffff0000, v3
	v_or_b32_sdwa v3, v5, v4 dst_sel:DWORD dst_unused:UNUSED_PAD src0_sel:DWORD src1_sel:WORD_1
	v_or_b32_sdwa v2, v6, v2 dst_sel:DWORD dst_unused:UNUSED_PAD src0_sel:DWORD src1_sel:WORD_1
	ds_write_b64 v157, v[2:3]
	s_waitcnt vmcnt(3)
	ds_write_b16 v158, v18 offset:34816
	ds_write_b16_d16_hi v158, v18 offset:35088
	ds_write_b16 v158, v19 offset:35360
	ds_write_b16_d16_hi v158, v19 offset:35632
	ds_write_b16 v158, v20 offset:35904
	ds_write_b16_d16_hi v158, v20 offset:36176
	ds_write_b16 v158, v21 offset:36448
	ds_write_b16_d16_hi v159, v21 offset:34816
	s_waitcnt vmcnt(2)
	ds_write_b16 v160, v14 offset:34816
	ds_write_b16_d16_hi v160, v14 offset:35088
	ds_write_b16 v160, v15 offset:35360
	ds_write_b16_d16_hi v160, v15 offset:35632
	ds_write_b16 v160, v16 offset:35904
	ds_write_b16_d16_hi v160, v16 offset:36176
	ds_write_b16 v160, v17 offset:36448
	ds_write_b16_d16_hi v161, v17 offset:34816
	s_waitcnt vmcnt(1)
	ds_write_b16 v162, v22 offset:34816
	ds_write_b16_d16_hi v162, v22 offset:35088
	ds_write_b16 v162, v23 offset:35360
	ds_write_b16_d16_hi v162, v23 offset:35632
	ds_write_b16 v162, v24 offset:35904
	ds_write_b16_d16_hi v162, v24 offset:36176
	ds_write_b16 v162, v25 offset:36448
	ds_write_b16_d16_hi v163, v25 offset:34816
	s_waitcnt vmcnt(0)
	ds_write_b16 v164, v10 offset:34816
	ds_write_b16_d16_hi v164, v10 offset:35088
	ds_write_b16 v164, v11 offset:35360
	ds_write_b16_d16_hi v164, v11 offset:35632
	ds_write_b16 v164, v12 offset:35904
	ds_write_b16_d16_hi v164, v12 offset:36176
	ds_write_b16 v164, v13 offset:36448
	ds_write_b16_d16_hi v165, v13 offset:34816
	v_cndmask_b32_e64 v2, 0, 1, s[86:87]
	v_cmp_ne_u32_e64 s[74:75], 1, v2
	s_waitcnt lgkmcnt(0)
	s_barrier
	v_readlane_b32 s98, v249, 24
	v_readlane_b32 s99, v249, 25
	v_readlane_b32 s100, v249, 20
	v_readlane_b32 s101, v249, 21
	v_add_u32_e32 v244, s96, v142
	v_lshlrev_b32_e32 v244, 2, v244
	v_or_b32_e32 v245, s96, v146
	v_lshlrev_b32_e32 v246, 2, v245
	v_add_u32_e32 v247, s33, v142
	v_lshlrev_b32_e32 v247, 12, v247
	v_lshl_add_u32 v247, v245, 1, v247
	global_load_dword v248, v244, s[98:99]
	global_load_dwordx4 v[180:183], v246, s[100:101]
	global_load_dwordx4 v[184:187], v246, s[100:101] offset:64
	global_load_dwordx4 v[188:191], v246, s[100:101] offset:128
	global_load_dwordx4 v[192:195], v246, s[100:101] offset:192
	global_load_dwordx4 v[196:199], v246, s[100:101] offset:256
	global_load_dwordx4 v[200:203], v246, s[100:101] offset:320
	global_load_dwordx4 v[204:207], v246, s[100:101] offset:384
	global_load_dwordx4 v[208:211], v246, s[100:101] offset:448
	global_load_dwordx2 v[212:213], v247, s[80:81]
	global_load_dwordx2 v[214:215], v247, s[80:81] offset:32
	global_load_dwordx2 v[216:217], v247, s[80:81] offset:64
	global_load_dwordx2 v[218:219], v247, s[80:81] offset:96
	global_load_dwordx2 v[220:221], v247, s[80:81] offset:128
	global_load_dwordx2 v[222:223], v247, s[80:81] offset:160
	global_load_dwordx2 v[224:225], v247, s[80:81] offset:192
	global_load_dwordx2 v[226:227], v247, s[80:81] offset:224
	v_readfirstlane_b32 s98, v178
	v_add_u32_e32 v70, v143, v144
	v_add_u32_e32 v71, v145, v148
	s_lshr_b32 s98, s98, 7
	s_add_i32 s98, s98, 1
	v_mov_b32_e32 v2, 0
	v_mov_b32_e32 v3, 0
	v_mov_b32_e32 v4, 0
	v_mov_b32_e32 v5, 0
	v_mov_b32_e32 v6, 0
	v_mov_b32_e32 v7, 0
	v_mov_b32_e32 v8, 0
	v_mov_b32_e32 v9, 0
	v_mov_b32_e32 v10, 0
	v_mov_b32_e32 v11, 0
	v_mov_b32_e32 v12, 0
	v_mov_b32_e32 v13, 0
	v_mov_b32_e32 v14, 0
	v_mov_b32_e32 v15, 0
	v_mov_b32_e32 v16, 0
	v_mov_b32_e32 v17, 0
	v_mov_b32_e32 v18, 0
	v_mov_b32_e32 v19, 0
	v_mov_b32_e32 v20, 0
	v_mov_b32_e32 v21, 0
	v_mov_b32_e32 v22, 0
	v_mov_b32_e32 v23, 0
	v_mov_b32_e32 v24, 0
	v_mov_b32_e32 v25, 0
	v_mov_b32_e32 v26, 0
	v_mov_b32_e32 v27, 0
	v_mov_b32_e32 v28, 0
	v_mov_b32_e32 v29, 0
	v_mov_b32_e32 v30, 0
	v_mov_b32_e32 v31, 0
	v_mov_b32_e32 v32, 0
	v_mov_b32_e32 v33, 0
	ds_read_b128 v[66:69], v70
	ds_read_b128 v[34:37], v71 offset:34816
	ds_read_b128 v[38:41], v71 offset:39168
	ds_read_b128 v[42:45], v71 offset:43520
	ds_read_b128 v[46:49], v71 offset:47872
	ds_read_b128 v[50:53], v71 offset:52224
	ds_read_b128 v[54:57], v71 offset:56576
	ds_read_b128 v[58:61], v71 offset:60928
	ds_read_b128 v[62:65], v71 offset:65280
	s_waitcnt lgkmcnt(0)
	v_mfma_f32_16x16x32_bf16 v[2:5], v[34:37], v[66:69], v[2:5]
	v_mfma_f32_16x16x32_bf16 v[6:9], v[38:41], v[66:69], v[6:9]
	v_mfma_f32_16x16x32_bf16 v[10:13], v[42:45], v[66:69], v[10:13]
	v_mfma_f32_16x16x32_bf16 v[14:17], v[46:49], v[66:69], v[14:17]
	v_mfma_f32_16x16x32_bf16 v[18:21], v[50:53], v[66:69], v[18:21]
	v_mfma_f32_16x16x32_bf16 v[22:25], v[54:57], v[66:69], v[22:25]
	v_mfma_f32_16x16x32_bf16 v[26:29], v[58:61], v[66:69], v[26:29]
	v_mfma_f32_16x16x32_bf16 v[30:33], v[62:65], v[66:69], v[30:33]
	s_cmp_lt_u32 s98, 2
	s_cbranch_scc1 .Lsgu_mm_done
	ds_read_b128 v[104:107], v70 offset:64
	ds_read_b128 v[72:75], v71 offset:34880
	ds_read_b128 v[76:79], v71 offset:39232
	ds_read_b128 v[80:83], v71 offset:43584
	ds_read_b128 v[84:87], v71 offset:47936
	ds_read_b128 v[88:91], v71 offset:52288
	ds_read_b128 v[92:95], v71 offset:56640
	ds_read_b128 v[96:99], v71 offset:60992
	ds_read_b128 v[100:103], v71 offset:65344
	s_waitcnt lgkmcnt(0)
	v_mfma_f32_16x16x32_bf16 v[2:5], v[72:75], v[104:107], v[2:5]
	v_mfma_f32_16x16x32_bf16 v[6:9], v[76:79], v[104:107], v[6:9]
	v_mfma_f32_16x16x32_bf16 v[10:13], v[80:83], v[104:107], v[10:13]
	v_mfma_f32_16x16x32_bf16 v[14:17], v[84:87], v[104:107], v[14:17]
	v_mfma_f32_16x16x32_bf16 v[18:21], v[88:91], v[104:107], v[18:21]
	v_mfma_f32_16x16x32_bf16 v[22:25], v[92:95], v[104:107], v[22:25]
	v_mfma_f32_16x16x32_bf16 v[26:29], v[96:99], v[104:107], v[26:29]
	v_mfma_f32_16x16x32_bf16 v[30:33], v[100:103], v[104:107], v[30:33]
	s_cmp_lt_u32 s98, 3
	s_cbranch_scc1 .Lsgu_mm_done
	ds_read_b128 v[66:69], v70 offset:128
	ds_read_b128 v[34:37], v71 offset:34944
	ds_read_b128 v[38:41], v71 offset:39296
	ds_read_b128 v[42:45], v71 offset:43648
	ds_read_b128 v[46:49], v71 offset:48000
	ds_read_b128 v[50:53], v71 offset:52352
	ds_read_b128 v[54:57], v71 offset:56704
	ds_read_b128 v[58:61], v71 offset:61056
	ds_read_b128 v[62:65], v71 offset:65408
	s_waitcnt lgkmcnt(0)
	v_mfma_f32_16x16x32_bf16 v[2:5], v[34:37], v[66:69], v[2:5]
	v_mfma_f32_16x16x32_bf16 v[6:9], v[38:41], v[66:69], v[6:9]
	v_mfma_f32_16x16x32_bf16 v[10:13], v[42:45], v[66:69], v[10:13]
	v_mfma_f32_16x16x32_bf16 v[14:17], v[46:49], v[66:69], v[14:17]
	v_mfma_f32_16x16x32_bf16 v[18:21], v[50:53], v[66:69], v[18:21]
	v_mfma_f32_16x16x32_bf16 v[22:25], v[54:57], v[66:69], v[22:25]
	v_mfma_f32_16x16x32_bf16 v[26:29], v[58:61], v[66:69], v[26:29]
	v_mfma_f32_16x16x32_bf16 v[30:33], v[62:65], v[66:69], v[30:33]
	s_cmp_lt_u32 s98, 4
	s_cbranch_scc1 .Lsgu_mm_done
	ds_read_b128 v[104:107], v70 offset:192
	ds_read_b128 v[72:75], v71 offset:35008
	ds_read_b128 v[76:79], v71 offset:39360
	ds_read_b128 v[80:83], v71 offset:43712
	ds_read_b128 v[84:87], v71 offset:48064
	ds_read_b128 v[88:91], v71 offset:52416
	ds_read_b128 v[92:95], v71 offset:56768
	ds_read_b128 v[96:99], v71 offset:61120
	ds_read_b128 v[100:103], v71 offset:65472
	s_waitcnt lgkmcnt(0)
	v_mfma_f32_16x16x32_bf16 v[2:5], v[72:75], v[104:107], v[2:5]
	v_mfma_f32_16x16x32_bf16 v[6:9], v[76:79], v[104:107], v[6:9]
	v_mfma_f32_16x16x32_bf16 v[10:13], v[80:83], v[104:107], v[10:13]
	v_mfma_f32_16x16x32_bf16 v[14:17], v[84:87], v[104:107], v[14:17]
	v_mfma_f32_16x16x32_bf16 v[18:21], v[88:91], v[104:107], v[18:21]
	v_mfma_f32_16x16x32_bf16 v[22:25], v[92:95], v[104:107], v[22:25]
	v_mfma_f32_16x16x32_bf16 v[26:29], v[96:99], v[104:107], v[26:29]
	v_mfma_f32_16x16x32_bf16 v[30:33], v[100:103], v[104:107], v[30:33]
.Lsgu_mm_done:
.LBB0_493:
	s_nop 7
	v_add_u32_e32 v244, s33, v142
	v_lshlrev_b32_e32 v244, 11, v244
	v_lshl_add_u32 v244, v245, 1, v244
	s_waitcnt vmcnt(0)
	v_fma_f32 v228, v2, v180, v248
	v_fma_f32 v229, v3, v181, v248
	v_fma_f32 v230, v4, v182, v248
	v_fma_f32 v231, v5, v183, v248
	v_lshlrev_b32_e32 v232, 16, v212
	v_and_b32_e32 v233, 0xffff0000, v212
	v_lshlrev_b32_e32 v234, 16, v213
	v_and_b32_e32 v235, 0xffff0000, v213
	v_mul_f32_e32 v228, v228, v232
	v_mul_f32_e32 v229, v229, v233
	v_mul_f32_e32 v230, v230, v234
	v_mul_f32_e32 v231, v231, v235
	v_cvt_pk_bf16_f32 v2, v228, v229
	v_cvt_pk_bf16_f32 v3, v230, v231
	v_fma_f32 v228, v6, v184, v248
	v_fma_f32 v229, v7, v185, v248
	v_fma_f32 v230, v8, v186, v248
	v_fma_f32 v231, v9, v187, v248
	v_lshlrev_b32_e32 v232, 16, v214
	v_and_b32_e32 v233, 0xffff0000, v214
	v_lshlrev_b32_e32 v234, 16, v215
	v_and_b32_e32 v235, 0xffff0000, v215
	v_mul_f32_e32 v228, v228, v232
	v_mul_f32_e32 v229, v229, v233
	v_mul_f32_e32 v230, v230, v234
	v_mul_f32_e32 v231, v231, v235
	v_cvt_pk_bf16_f32 v6, v228, v229
	v_cvt_pk_bf16_f32 v7, v230, v231
	v_fma_f32 v228, v10, v188, v248
	v_fma_f32 v229, v11, v189, v248
	v_fma_f32 v230, v12, v190, v248
	v_fma_f32 v231, v13, v191, v248
	v_lshlrev_b32_e32 v232, 16, v216
	v_and_b32_e32 v233, 0xffff0000, v216
	v_lshlrev_b32_e32 v234, 16, v217
	v_and_b32_e32 v235, 0xffff0000, v217
	v_mul_f32_e32 v228, v228, v232
	v_mul_f32_e32 v229, v229, v233
	v_mul_f32_e32 v230, v230, v234
	v_mul_f32_e32 v231, v231, v235
	v_cvt_pk_bf16_f32 v10, v228, v229
	v_cvt_pk_bf16_f32 v11, v230, v231
	v_fma_f32 v228, v14, v192, v248
	v_fma_f32 v229, v15, v193, v248
	v_fma_f32 v230, v16, v194, v248
	v_fma_f32 v231, v17, v195, v248
	v_lshlrev_b32_e32 v232, 16, v218
	v_and_b32_e32 v233, 0xffff0000, v218
	v_lshlrev_b32_e32 v234, 16, v219
	v_and_b32_e32 v235, 0xffff0000, v219
	v_mul_f32_e32 v228, v228, v232
	v_mul_f32_e32 v229, v229, v233
	v_mul_f32_e32 v230, v230, v234
	v_mul_f32_e32 v231, v231, v235
	v_cvt_pk_bf16_f32 v14, v228, v229
	v_cvt_pk_bf16_f32 v15, v230, v231
	v_fma_f32 v228, v18, v196, v248
	v_fma_f32 v229, v19, v197, v248
	v_fma_f32 v230, v20, v198, v248
	v_fma_f32 v231, v21, v199, v248
	v_lshlrev_b32_e32 v232, 16, v220
	v_and_b32_e32 v233, 0xffff0000, v220
	v_lshlrev_b32_e32 v234, 16, v221
	v_and_b32_e32 v235, 0xffff0000, v221
	v_mul_f32_e32 v228, v228, v232
	v_mul_f32_e32 v229, v229, v233
	v_mul_f32_e32 v230, v230, v234
	v_mul_f32_e32 v231, v231, v235
	v_cvt_pk_bf16_f32 v18, v228, v229
	v_cvt_pk_bf16_f32 v19, v230, v231
	v_fma_f32 v228, v22, v200, v248
	v_fma_f32 v229, v23, v201, v248
	v_fma_f32 v230, v24, v202, v248
	v_fma_f32 v231, v25, v203, v248
	v_lshlrev_b32_e32 v232, 16, v222
	v_and_b32_e32 v233, 0xffff0000, v222
	v_lshlrev_b32_e32 v234, 16, v223
	v_and_b32_e32 v235, 0xffff0000, v223
	v_mul_f32_e32 v228, v228, v232
	v_mul_f32_e32 v229, v229, v233
	v_mul_f32_e32 v230, v230, v234
	v_mul_f32_e32 v231, v231, v235
	v_cvt_pk_bf16_f32 v22, v228, v229
	v_cvt_pk_bf16_f32 v23, v230, v231
	v_fma_f32 v228, v26, v204, v248
	v_fma_f32 v229, v27, v205, v248
	v_fma_f32 v230, v28, v206, v248
	v_fma_f32 v231, v29, v207, v248
	v_lshlrev_b32_e32 v232, 16, v224
	v_and_b32_e32 v233, 0xffff0000, v224
	v_lshlrev_b32_e32 v234, 16, v225
	v_and_b32_e32 v235, 0xffff0000, v225
	v_mul_f32_e32 v228, v228, v232
	v_mul_f32_e32 v229, v229, v233
	v_mul_f32_e32 v230, v230, v234
	v_mul_f32_e32 v231, v231, v235
	v_cvt_pk_bf16_f32 v26, v228, v229
	v_cvt_pk_bf16_f32 v27, v230, v231
	v_fma_f32 v228, v30, v208, v248
	v_fma_f32 v229, v31, v209, v248
	v_fma_f32 v230, v32, v210, v248
	v_fma_f32 v231, v33, v211, v248
	v_lshlrev_b32_e32 v232, 16, v226
	v_and_b32_e32 v233, 0xffff0000, v226
	v_lshlrev_b32_e32 v234, 16, v227
	v_and_b32_e32 v235, 0xffff0000, v227
	v_mul_f32_e32 v228, v228, v232
	v_mul_f32_e32 v229, v229, v233
	v_mul_f32_e32 v230, v230, v234
	v_mul_f32_e32 v231, v231, v235
	v_cvt_pk_bf16_f32 v30, v228, v229
	v_cvt_pk_bf16_f32 v31, v230, v231
	s_cmp_lt_u32 s89, 3
	s_cbranch_scc1 .Lsgu_st_plain
	global_store_dwordx2 v244, v[2:3], s[82:83] sc1
	global_store_dwordx2 v244, v[6:7], s[82:83] offset:32 sc1
	global_store_dwordx2 v244, v[10:11], s[82:83] offset:64 sc1
	global_store_dwordx2 v244, v[14:15], s[82:83] offset:96 sc1
	global_store_dwordx2 v244, v[18:19], s[82:83] offset:128 sc1
	global_store_dwordx2 v244, v[22:23], s[82:83] offset:160 sc1
	global_store_dwordx2 v244, v[26:27], s[82:83] offset:192 sc1
	global_store_dwordx2 v244, v[30:31], s[82:83] offset:224 sc1
	s_branch .LBB0_431
.Lsgu_st_plain:
	global_store_dwordx2 v244, v[2:3], s[82:83]
	global_store_dwordx2 v244, v[6:7], s[82:83] offset:32
	global_store_dwordx2 v244, v[10:11], s[82:83] offset:64
	global_store_dwordx2 v244, v[14:15], s[82:83] offset:96
	global_store_dwordx2 v244, v[18:19], s[82:83] offset:128
	global_store_dwordx2 v244, v[22:23], s[82:83] offset:160
	global_store_dwordx2 v244, v[26:27], s[82:83] offset:192
	global_store_dwordx2 v244, v[30:31], s[82:83] offset:224
	s_branch .LBB0_431

.LBB0_1397:
	s_andn2_b64 vcc, exec, s[0:1]
	s_cbranch_vccnz .LBB0_1464
	v_readlane_b32 s0, v249, 4
	v_readlane_b32 s1, v249, 5
	s_cmpk_lt_u32 s1, 0x3e9
	s_mov_b64 s[0:1], -1
	s_cbranch_scc0 .LBB0_1452
	v_readlane_b32 s2, v249, 2
	s_cmpk_eq_i32 s2, 0x100
	s_cbranch_scc0 .Lg7_xcd
	s_waitcnt vmcnt(0)
	s_waitcnt vmcnt(0) lgkmcnt(0)
	s_barrier
	s_mov_b64 s[0:1], exec
	v_readlane_b32 s2, v249, 10
	v_readlane_b32 s3, v249, 11
	s_and_b64 s[2:3], s[0:1], s[2:3]
	s_mov_b64 exec, s[2:3]
	s_cbranch_execz .Lg7_BB0_1004
	s_lshl_b32 s2, s81, 8
	s_and_b32 s2, s2, 0x3f00
	s_mov_b64 s[4:5], exec
	s_add_u32 s2, s82, s2
	s_addc_u32 s3, s83, 0
	v_readlane_b32 s98, v250, 0
	s_cmp_lg_u32 s98, 0
	s_cbranch_scc1 .Lg7_skip_wbl2_2
	buffer_wbl2 sc1

.Lg7_BB0_1004:
	s_or_b64 exec, exec, s[0:1]
	s_barrier
	s_mov_b64 s[0:1], 0
	s_branch .LBB0_1452
.Lg7_xcd:
	s_waitcnt vmcnt(0)
	s_waitcnt vmcnt(0) lgkmcnt(0)
	s_barrier
	s_mov_b64 s[0:1], exec
	v_readlane_b32 s2, v249, 10
	v_readlane_b32 s3, v249, 11
	s_and_b64 s[2:3], s[0:1], s[2:3]
	s_mov_b64 exec, s[2:3]
	s_cbranch_execz .LBB0_1451
	s_add_i32 s2, 0, 0x20160
	v_mov_b32_e32 v1, s2
	s_waitcnt vmcnt(0) expcnt(0) lgkmcnt(0)
	ds_read_b32 v3, v1
	s_add_i32 s2, 0, 0x20164
	v_mov_b32_e32 v1, s2
	ds_read_b32 v1, v1
	s_waitcnt lgkmcnt(1)
	v_cmp_ne_u32_e32 vcc, 0, v3
	s_cbranch_vccnz .LBB0_1415
	v_readlane_b32 s2, v249, 2
	v_readlane_b32 s3, v249, 3
	v_readlane_b32 s4, v249, 6
	s_mul_i32 s33, s3, s4
	s_mul_i32 s33, s33, s2
	s_add_u32 s2, s82, 0x4200
	s_addc_u32 s3, s83, 0
	s_add_u32 s4, s82, 0x4400
	s_addc_u32 s5, s83, 0
	s_add_u32 s6, s82, 0x4500
	s_addc_u32 s7, s83, 0
	s_add_u32 s8, s82, 0x4600
	s_addc_u32 s9, s83, 0
	s_add_u32 s10, s82, 0x4700
	s_addc_u32 s11, s83, 0
	s_add_u32 s12, s82, 0x4800
	s_addc_u32 s13, s83, 0
	s_add_u32 s14, s82, 0x4900
	s_addc_u32 s15, s83, 0
	s_add_u32 s16, s82, 0x4a00
	s_addc_u32 s17, s83, 0
	s_add_u32 s18, s82, 0x4b00
	s_addc_u32 s19, s83, 0
	s_add_u32 s20, s82, 0x4c00
	s_addc_u32 s21, s83, 0
	s_add_u32 s22, s82, 0x4d00
	s_addc_u32 s23, s83, 0
	s_add_u32 s24, s82, 0x4e00
	s_addc_u32 s25, s83, 0
	s_add_u32 s26, s82, 0x4f00
	s_addc_u32 s27, s83, 0
	s_add_u32 s28, s82, 0x5000
	s_addc_u32 s29, s83, 0
	s_add_u32 s30, s82, 0x5100
	s_addc_u32 s31, s83, 0
	s_add_u32 s34, s82, 0x5200
	s_addc_u32 s35, s83, 0
	s_add_u32 s36, s82, 0x5300
	s_addc_u32 s37, s83, 0
	s_mov_b32 s44, 1
	v_mov_b32_e32 v17, 0
	s_branch .LBB0_1403
